# attention: next-tile global prefetch issued behind the step's first K-fragment LDS reads
# speedup vs baseline: 1.0109x; 1.0000x over previous
; __device__ __forceinline__ void attn_qk(f32x16& p0, f32x16& p1, const bf16x8 (&kf)[12], const bf16x8 (&qf)[6]) {
;     const f32x16 zero = {0.f, 0.f, 0.f, 0.f, 0.f, 0.f, 0.f, 0.f, 0.f, 0.f, 0.f, 0.f, 0.f, 0.f, 0.f, 0.f};
; #pragma unroll
;     for (int ks = 0; ks < 6; ++ks) {
;         p0 = __builtin_amdgcn_mfma_f32_32x32x16_bf16(kf[2 * ks], qf[ks], ks == 0 ? zero : p0, 0, 0, 0);
;         p1 = __builtin_amdgcn_mfma_f32_32x32x16_bf16(kf[2 * ks + 1], qf[ks], ks == 0 ? zero : p1, 0, 0, 0);
;     }
; }
; __device__ __forceinline__ void attn_softmax(f32x16& p0, f32x16& p1, bf16x8 (&pb)[4], f32x16& o0, f32x16& o1, float& m_run, float& l_run) {
;     float mx = max3f(p0[0], p0[1], p1[0]), my = max3f(p0[2], p0[3], p1[1]);
;     mx = max3f(mx, p1[2], p1[3]);
; #pragma unroll
;     for (int r = 4; r < 16; r += 4) { mx = max3f(mx, p0[r], p0[r + 1]); my = max3f(my, p0[r + 2], p0[r + 3]); mx = max3f(mx, p1[r], p1[r + 1]); my = max3f(my, p1[r + 2], p1[r + 3]); }
;     mx = fmaxf(mx, my);
;     { auto rr = __builtin_amdgcn_permlane32_swap(__float_as_uint(mx), __float_as_uint(mx), false, false); mx = fmaxf(__uint_as_float(rr[0]), __uint_as_float(rr[1])); }
;     const float m_new = fmaxf(m_run, mx);
;     const float alpha = __builtin_amdgcn_exp2f(m_run - m_new);
; __device__ __forceinline__ void attn_phase(LAS unsigned char* lds, const bf16_t* __restrict__ Q, const bf16_t* __restrict__ KN, const bf16_t* __restrict__ KR,
;                                            const bf16_t* __restrict__ VT, bf16_t* AO, int vcu, int G, int tid, int lane, int wave) {
;     ...
;             for (int t = 0; t < NT2; ++t) {
;                 const bool more = (t + 1 < NT2);
;                 const LAS unsigned char* buf = lds + (t & 1) * BUF;
;                 const LAS unsigned char* kA = buf + (pr * KP + 8 * hi) * 2; const LAS unsigned char* vA = buf + KBUF + (r32 * VP + 8 * hi) * 2;
;                 if (2 * t + 1 <= qc) {
;                     bf16x8 kf[12], kf2[12], vf[8], vf2[8], pa[4], pb2[4]; f32x16 a0, a1, b0, b1;
;                     attn_ldk(kf, kA);
;                     __builtin_amdgcn_sched_barrier(0);
;                     attn_qk(a0, a1, kf, qf);
;                     attn_ldk(kf2, kA + 64 * KP * 2);
;                     __builtin_amdgcn_sched_barrier(0);
;                     attn_qk(b0, b1, kf2, qf);
;                     attn_softmax(a0, a1, pa, o0, o1, m_run, l_run);
.Lat_step:
	s_add_i32 s39, s8, 1
	s_bitcmp1_b32 s8, 0
	s_cselect_b32 s37, 0xac00, 0
	s_cselect_b32 s38, 0, 0xac00
	s_lshl_b32 s40, s8, 1
	s_cmp_lt_u32 s40, s33
	s_cbranch_scc1 .Lat_both
	s_cmp_eq_u32 s40, s33
	s_cbranch_scc1 .Lat_single
	s_branch .Lat_tail
.Lat_both:
	v_add_u32_e32 v1, s37, v222
	v_add_u32_e32 v225, s37, v223
	ds_read_b128 v[138:141], v1
	ds_read_b128 v[142:145], v1 offset:6656
	ds_read_b128 v[146:149], v1 offset:32
	ds_read_b128 v[150:153], v1 offset:6688
	ds_read_b128 v[154:157], v1 offset:64
	ds_read_b128 v[158:161], v1 offset:6720
	ds_read_b128 v[162:165], v1 offset:96
	ds_read_b128 v[166:169], v1 offset:6752
	s_cmp_lt_u32 s39, s36
	s_cbranch_scc0 .Lat_nopf_2
	s_mov_b32 s40, s39
	s_mov_b32 s41, 0
	s_lshl_b64 s[14:15], s[40:41], 17
	s_add_u32 s14, s10, s14
	s_addc_u32 s15, s11, s15
	global_load_dwordx4 v[228:231], v198, s[14:15]
	s_add_u32 s14, s14, 0x10000
	s_addc_u32 s15, s15, 0
	global_load_dwordx4 v[232:235], v198, s[14:15]
	s_lshl_b64 s[14:15], s[40:41], 13
	v_lshl_add_u64 v[250:251], v[208:209], 0, s[14:15]
	s_lshl_b64 s[14:15], s[40:41], 8
	v_lshl_add_u64 v[252:253], v[210:211], 0, s[14:15]
	global_load_dwordx4 v[236:239], v[250:251], off
	global_load_dwordx4 v[240:243], v[252:253], off
	global_load_dwordx4 v[244:247], v[252:253], off offset:128
.Lat_nopf_2:
	s_waitcnt vmcnt(5)
	s_waitcnt lgkmcnt(7)
	v_mfma_f32_32x32x16_bf16 v[34:49], v[138:141], v[114:117], v[98:113]
	ds_read_b128 v[138:141], v1 offset:128
	s_waitcnt lgkmcnt(7)
	v_mfma_f32_32x32x16_bf16 v[50:65], v[142:145], v[114:117], v[98:113]
	ds_read_b128 v[142:145], v1 offset:6784
	s_waitcnt lgkmcnt(7)
	v_mfma_f32_32x32x16_bf16 v[34:49], v[146:149], v[118:121], v[34:49]
	ds_read_b128 v[146:149], v1 offset:160
	s_waitcnt lgkmcnt(7)
	v_mfma_f32_32x32x16_bf16 v[50:65], v[150:153], v[118:121], v[50:65]
	ds_read_b128 v[150:153], v1 offset:6816
	s_waitcnt lgkmcnt(7)
	v_mfma_f32_32x32x16_bf16 v[34:49], v[154:157], v[122:125], v[34:49]
	ds_read_b128 v[154:157], v1 offset:13312
	s_waitcnt lgkmcnt(7)
	v_mfma_f32_32x32x16_bf16 v[50:65], v[158:161], v[122:125], v[50:65]
	ds_read_b128 v[158:161], v1 offset:19968
	s_waitcnt lgkmcnt(7)
	v_mfma_f32_32x32x16_bf16 v[34:49], v[162:165], v[126:129], v[34:49]
	ds_read_b128 v[162:165], v1 offset:13344
	s_waitcnt lgkmcnt(7)
	v_mfma_f32_32x32x16_bf16 v[50:65], v[166:169], v[126:129], v[50:65]
	ds_read_b128 v[166:169], v1 offset:20000
	s_waitcnt lgkmcnt(7)
	v_mfma_f32_32x32x16_bf16 v[34:49], v[138:141], v[130:133], v[34:49]
	ds_read_b128 v[138:141], v1 offset:13376
	s_waitcnt lgkmcnt(7)
	v_mfma_f32_32x32x16_bf16 v[50:65], v[142:145], v[130:133], v[50:65]
	ds_read_b128 v[142:145], v1 offset:20032
	s_waitcnt lgkmcnt(7)
	v_mfma_f32_32x32x16_bf16 v[34:49], v[146:149], v[134:137], v[34:49]
	ds_read_b128 v[146:149], v1 offset:13408
	s_waitcnt lgkmcnt(7)
	v_mfma_f32_32x32x16_bf16 v[50:65], v[150:153], v[134:137], v[50:65]
	ds_read_b128 v[150:153], v1 offset:20064
	s_cmp_lg_u32 s7, 0
	s_cbranch_scc1 .Lat_plain_A2
	s_waitcnt lgkmcnt(7)
	v_mfma_f32_32x32x16_bf16 v[66:81], v[154:157], v[114:117], v[98:113]
	ds_read_b128 v[154:157], v1 offset:13440
	s_waitcnt lgkmcnt(7)
	v_mfma_f32_32x32x16_bf16 v[82:97], v[158:161], v[114:117], v[98:113]
	ds_read_b128 v[158:161], v1 offset:20096
	s_waitcnt lgkmcnt(7)
	v_mfma_f32_32x32x16_bf16 v[66:81], v[162:165], v[118:121], v[66:81]
	ds_read_b128 v[162:165], v1 offset:13472
	v_exp_f32_e32 v34, v34
	v_exp_f32_e32 v50, v50
	v_exp_f32_e32 v35, v35
	v_exp_f32_e32 v51, v51
	s_waitcnt lgkmcnt(7)
	v_mfma_f32_32x32x16_bf16 v[82:97], v[166:169], v[118:121], v[82:97]
	ds_read_b128 v[166:169], v1 offset:20128
	v_exp_f32_e32 v36, v36
	v_exp_f32_e32 v52, v52
	v_exp_f32_e32 v37, v37
	v_exp_f32_e32 v53, v53
	s_waitcnt lgkmcnt(7)
	v_mfma_f32_32x32x16_bf16 v[66:81], v[138:141], v[122:125], v[66:81]
	ds_read_b128 v[170:173], v225 offset:26624
	v_exp_f32_e32 v38, v38
	v_exp_f32_e32 v54, v54
	v_exp_f32_e32 v39, v39
	s_waitcnt lgkmcnt(7)
	v_mfma_f32_32x32x16_bf16 v[82:97], v[142:145], v[122:125], v[82:97]
	ds_read_b128 v[174:177], v225 offset:35328
	v_exp_f32_e32 v55, v55
	v_exp_f32_e32 v40, v40
	v_exp_f32_e32 v56, v56
	s_waitcnt lgkmcnt(7)
	v_mfma_f32_32x32x16_bf16 v[66:81], v[146:149], v[126:129], v[66:81]
	ds_read_b128 v[178:181], v225 offset:26656
	v_exp_f32_e32 v41, v41
	v_exp_f32_e32 v57, v57
	v_exp_f32_e32 v42, v42
	s_waitcnt lgkmcnt(7)
	v_mfma_f32_32x32x16_bf16 v[82:97], v[150:153], v[126:129], v[82:97]
	ds_read_b128 v[182:185], v225 offset:35360
	v_exp_f32_e32 v58, v58
	v_exp_f32_e32 v43, v43
	v_exp_f32_e32 v59, v59
	s_waitcnt lgkmcnt(7)
	v_mfma_f32_32x32x16_bf16 v[66:81], v[154:157], v[130:133], v[66:81]
	ds_read_b128 v[186:189], v225 offset:26688
	v_exp_f32_e32 v44, v44
	v_exp_f32_e32 v60, v60
	v_exp_f32_e32 v45, v45
	s_waitcnt lgkmcnt(7)
	v_mfma_f32_32x32x16_bf16 v[82:97], v[158:161], v[130:133], v[82:97]
	ds_read_b128 v[190:193], v225 offset:35392
	v_exp_f32_e32 v61, v61
	v_exp_f32_e32 v46, v46
	v_exp_f32_e32 v62, v62
	s_waitcnt lgkmcnt(7)
	v_mfma_f32_32x32x16_bf16 v[66:81], v[162:165], v[134:137], v[66:81]
	v_exp_f32_e32 v47, v47
	v_exp_f32_e32 v63, v63
	v_exp_f32_e32 v48, v48
	s_waitcnt lgkmcnt(6)
	v_mfma_f32_32x32x16_bf16 v[82:97], v[166:169], v[134:137], v[82:97]
	v_exp_f32_e32 v64, v64
	v_exp_f32_e32 v49, v49
	v_exp_f32_e32 v65, v65
	s_mov_b32 s41, 0
	s_branch .Lat_sum_A2

; __device__ __forceinline__ void attn_qk(f32x16& p0, f32x16& p1, const bf16x8 (&kf)[12], const bf16x8 (&qf)[6]) {
;     const f32x16 zero = {0.f, 0.f, 0.f, 0.f, 0.f, 0.f, 0.f, 0.f, 0.f, 0.f, 0.f, 0.f, 0.f, 0.f, 0.f, 0.f};
; #pragma unroll
;     for (int ks = 0; ks < 6; ++ks) {
;         p0 = __builtin_amdgcn_mfma_f32_32x32x16_bf16(kf[2 * ks], qf[ks], ks == 0 ? zero : p0, 0, 0, 0);
;         p1 = __builtin_amdgcn_mfma_f32_32x32x16_bf16(kf[2 * ks + 1], qf[ks], ks == 0 ? zero : p1, 0, 0, 0);
;     }
; }
; __device__ __forceinline__ void attn_phase(LAS unsigned char* lds, const bf16_t* __restrict__ Q, const bf16_t* __restrict__ KN, const bf16_t* __restrict__ KR,
;                                            const bf16_t* __restrict__ VT, bf16_t* AO, int vcu, int G, int tid, int lane, int wave) {
;     ...
;                 } else if (2 * t <= qc) {
;                     bf16x8 kf[12], vf[8], pa[4]; f32x16 a0, a1;
;                     PREFETCH_NEXT();
;                     attn_ldk(kf, kA);
;                     __builtin_amdgcn_sched_barrier(0);
;                     attn_qk(a0, a1, kf, qf);
;                     __builtin_amdgcn_sched_barrier(0);
;                     attn_ldv(vf, vA);
;                     __builtin_amdgcn_sched_barrier(0);
;                     attn_softmax(a0, a1, pa, o0, o1, m_run, l_run);
;                     __builtin_amdgcn_sched_barrier(0);
;                     attn_pv(vf, pa, o0, o1);
.Lat_nopf_1:
	s_waitcnt vmcnt(5)
	s_waitcnt lgkmcnt(7)
	v_mfma_f32_32x32x16_bf16 v[34:49], v[138:141], v[114:117], v[98:113]
	ds_read_b128 v[138:141], v1 offset:128
	s_waitcnt lgkmcnt(7)
	v_mfma_f32_32x32x16_bf16 v[50:65], v[142:145], v[114:117], v[98:113]
	ds_read_b128 v[142:145], v1 offset:6784
	s_waitcnt lgkmcnt(7)
	v_mfma_f32_32x32x16_bf16 v[34:49], v[146:149], v[118:121], v[34:49]
	ds_read_b128 v[146:149], v1 offset:160
	s_waitcnt lgkmcnt(7)
	v_mfma_f32_32x32x16_bf16 v[50:65], v[150:153], v[118:121], v[50:65]
	ds_read_b128 v[150:153], v1 offset:6816
	s_waitcnt lgkmcnt(7)
	v_mfma_f32_32x32x16_bf16 v[34:49], v[154:157], v[122:125], v[34:49]
	ds_read_b128 v[170:173], v225 offset:26624
	s_waitcnt lgkmcnt(7)
	v_mfma_f32_32x32x16_bf16 v[50:65], v[158:161], v[122:125], v[50:65]
	ds_read_b128 v[174:177], v225 offset:35328
	s_waitcnt lgkmcnt(7)
	v_mfma_f32_32x32x16_bf16 v[34:49], v[162:165], v[126:129], v[34:49]
	ds_read_b128 v[178:181], v225 offset:26656
	s_waitcnt lgkmcnt(7)
	v_mfma_f32_32x32x16_bf16 v[50:65], v[166:169], v[126:129], v[50:65]
	ds_read_b128 v[182:185], v225 offset:35360
	s_waitcnt lgkmcnt(7)
	v_mfma_f32_32x32x16_bf16 v[34:49], v[138:141], v[130:133], v[34:49]
	ds_read_b128 v[186:189], v225 offset:26688
	s_waitcnt lgkmcnt(7)
	v_mfma_f32_32x32x16_bf16 v[50:65], v[142:145], v[130:133], v[50:65]
	ds_read_b128 v[190:193], v225 offset:35392
	s_waitcnt lgkmcnt(7)
	v_mfma_f32_32x32x16_bf16 v[34:49], v[146:149], v[134:137], v[34:49]
	s_waitcnt lgkmcnt(6)
	v_mfma_f32_32x32x16_bf16 v[50:65], v[150:153], v[134:137], v[50:65]
	s_mov_b32 s41, 0
	s_cmp_lg_u32 s7, 0
	s_cbranch_scc1 .Lat_first_A1

; #define LAS __attribute__((address_space(3)))
; __device__ __forceinline__ void attn_phase(LAS unsigned char* lds, const bf16_t* __restrict__ Q, const bf16_t* __restrict__ KN, const bf16_t* __restrict__ KR,
;                                            const bf16_t* __restrict__ VT, bf16_t* AO, int vcu, int G, int tid, int lane, int wave) {
;     ...
;                 } else { PREFETCH_NEXT(); }
;                 if (more) { LAS unsigned char* nb = lds + ((t + 1) & 1) * BUF;
;                     *(LAS u32x4*)(nb + kdst) = gk0; *(LAS u32x4*)(nb + kdst + 64 * KP * 2) = gk1; *(LAS u32x4*)(nb + rdst) = gr; *(LAS u32x4*)(nb + vdst) = gv0; *(LAS u32x4*)(nb + vdst + 128) = gv1; }
;                 __syncthreads();
.Lat_tail:
	s_cmp_lt_u32 s39, s36
	s_cbranch_scc0 .Lat_nostage
	s_mov_b32 s40, s39
	s_mov_b32 s41, 0
	s_lshl_b64 s[14:15], s[40:41], 17
	s_add_u32 s14, s10, s14
	s_addc_u32 s15, s11, s15
	global_load_dwordx4 v[228:231], v198, s[14:15]
	s_add_u32 s14, s14, 0x10000
	s_addc_u32 s15, s15, 0
	global_load_dwordx4 v[232:235], v198, s[14:15]
	s_lshl_b64 s[14:15], s[40:41], 13
	v_lshl_add_u64 v[250:251], v[208:209], 0, s[14:15]
	s_lshl_b64 s[14:15], s[40:41], 8
	v_lshl_add_u64 v[252:253], v[210:211], 0, s[14:15]
	global_load_dwordx4 v[236:239], v[250:251], off
	global_load_dwordx4 v[240:243], v[252:253], off
	global_load_dwordx4 v[244:247], v[252:253], off offset:128
	s_waitcnt vmcnt(0)
	v_add_u32_e32 v1, s38, v219
	ds_write_b128 v1, v[228:231]
	ds_write_b128 v1, v[232:235] offset:13312
	v_add_u32_e32 v1, s38, v220
	ds_write_b128 v1, v[236:239]
	v_add_u32_e32 v1, s38, v221
	ds_write_b128 v1, v[240:243] offset:26624
	ds_write_b128 v1, v[244:247] offset:26752
